# loop-edge edit: Epi K-loop head pointer selects moved behind the first fragment reads
# baseline (speedup 1.0000x reference)
; #define PG8_STAGE(bufoff, gbase, voff) do { _Pragma("unroll") for (int _i = 0; _i < 2; ++_i) \
;         __builtin_amdgcn_global_load_lds((const unsigned*)((const char*)(gbase) + (voff)[_i]), (PG8_LAS unsigned*)(lds + (bufoff) + ldsw + _i * 8192), 16, 0, 0); } while (0)
; #define PG8_LDA(dst, b, h) do { _Pragma("unroll") for (int m = 0; m < 4; ++m) _Pragma("unroll") for (int k = 0; k < 2; ++k) dst[m][k] = *(const PG8_LAS bf16x8*)(lds + PG8_SA(b, h) + aoff + m * 2048 + k * 1024); } while (0)
; #define PG8_LDB(dst, b, h) do { _Pragma("unroll") for (int n = 0; n < 2; ++n) _Pragma("unroll") for (int k = 0; k < 2; ++k) dst[n][k] = *(const PG8_LAS bf16x8*)(lds + PG8_SB(b, h) + boff + n * 2048 + k * 1024); } while (0)
; #define PG8_MMA(ai, bj, At, Bt) do { __builtin_amdgcn_s_setprio(1); _Pragma("unroll") for (int m = 0; m < 4; ++m) _Pragma("unroll") for (int n = 0; n < 2; ++n) _Pragma("unroll") for (int k = 0; k < 2; ++k) \
;         acc[ai][bj][m][n] = __builtin_amdgcn_mfma_f32_16x16x32_bf16(Bt[n][k], At[m][k], acc[ai][bj][m][n], 0, 0, 0); __builtin_amdgcn_s_setprio(0); } while (0)
; #define PG8_WAIT_V(n) asm volatile("s_waitcnt vmcnt(" #n ")" ::: "memory")
; #define PG8_WAIT_L(n) asm volatile("s_waitcnt lgkmcnt(" #n ")" ::: "memory")
; template <class Epi, class Sched, bool ALIGN_EPI = false, bool SP2 = false>
; __device__ __forceinline__ void gemm_phase(PG8_LAS unsigned char* lds, const Gemm g, const Sched& S, const Epi& E, const int wid_) {
;     ...
;             const bool last = (t == nt - 2);
;             const char* a1 = cA + (size_t)(t + 1) * kstep;
;             const char* a2 = last ? nA : cA + (size_t)(t + 2) * kstep; const char* b2 = last ? nB : cB + (size_t)(t + 2) * kstep;
;             const char* a3 = a2 + kstep; const char* b3 = b2 + kstep;
;             if (last && has_next) S.a_ready(nxt);
;             if constexpr (SP2) {
;             PG8_LDB(B0, 0, 0); PG8_LDB(B1, 0, 1); PG8_SCHED; PG8_LDA(At, 0, 0); PG8_STAGE(PG8_SA(1, 1), a1 + hstepA, voffA);
;             PG8_WAIT_V(8); PG8_WAIT_L(0); PG8_BAR; PG8_MMA(0, 0, At, B0); PG8_MMA(0, 1, At, B1); PG8_BAR; PG8_SCHED;
;             PG8_LDA(At, 0, 1); PG8_STAGE(PG8_SB(0, 0), b2, voffB); PG8_STAGE(PG8_SB(0, 1), b2 + hstepB, voffB); PG8_STAGE(PG8_SA(0, 0), a2, voffA);
;             PG8_WAIT_V(8); PG8_WAIT_L(0); PG8_BAR; PG8_MMA(1, 0, At, B0); PG8_MMA(1, 1, At, B1); PG8_BAR; PG8_SCHED;
.LBB0_380:
	s_add_i32 vcc_lo, 0, 0x14000
	v_add_u32_e32 v164, s42, v180
	v_add_u32_e32 v176, vcc_lo, v180
	ds_read_b128 v[128:131], v164
	ds_read_b128 v[132:135], v164 offset:1024
	ds_read_b128 v[136:139], v164 offset:2048
	ds_read_b128 v[164:167], v164 offset:3072
	ds_read_b128 v[168:171], v176
	ds_read_b128 v[172:175], v176 offset:1024
	ds_read_b128 v[182:185], v176 offset:2048
	ds_read_b128 v[186:189], v176 offset:3072
	s_add_i32 s97, s38, 2
	s_add_u32 s98, s6, 0x80
	s_addc_u32 s39, s7, 0
	s_cmp_eq_u32 s41, s38
	s_cselect_b32 s39, s47, s39
	s_cselect_b32 s38, s46, s98
	s_cselect_b32 s99, s61, s62
	s_cselect_b32 s98, s60, s49
	v_lshl_add_u64 v[178:179], s[6:7], 0, v[162:163]
	s_add_i32 m0, s36, 0xc000
	ds_read_b128 v[190:193], v181
	ds_read_b128 v[194:197], v181 offset:1024
	ds_read_b128 v[198:201], v181 offset:2048
	ds_read_b128 v[202:205], v181 offset:3072
	ds_read_b128 v[206:209], v181 offset:4096
	ds_read_b128 v[212:215], v181 offset:5120
	ds_read_b128 v[216:219], v181 offset:6144
	ds_read_b128 v[220:223], v181 offset:7168
	global_load_lds_dwordx4 v[178:179], off
	v_lshl_add_u64 v[178:179], s[6:7], 0, v[160:161]
	s_add_i32 m0, s36, 0xe000
	s_nop 0
	global_load_lds_dwordx4 v[178:179], off
	s_waitcnt vmcnt(8)
	s_waitcnt lgkmcnt(0)
	s_barrier
	s_waitcnt lgkmcnt(0)
	v_mfma_f32_16x16x32_bf16 v[124:127], v[128:131], v[190:193], v[124:127]
	v_mfma_f32_16x16x32_bf16 v[120:123], v[136:139], v[190:193], v[120:123]
	v_mfma_f32_16x16x32_bf16 v[116:119], v[128:131], v[198:201], v[116:119]
	v_mfma_f32_16x16x32_bf16 v[112:115], v[136:139], v[198:201], v[112:115]
	v_mfma_f32_16x16x32_bf16 v[100:103], v[128:131], v[206:209], v[100:103]
	v_mfma_f32_16x16x32_bf16 v[96:99], v[136:139], v[206:209], v[96:99]
	v_mfma_f32_16x16x32_bf16 v[84:87], v[128:131], v[216:219], v[84:87]
	v_mfma_f32_16x16x32_bf16 v[80:83], v[136:139], v[216:219], v[80:83]
	v_mfma_f32_16x16x32_bf16 v[124:127], v[132:135], v[194:197], v[124:127]
	v_mfma_f32_16x16x32_bf16 v[120:123], v[164:167], v[194:197], v[120:123]
	v_mfma_f32_16x16x32_bf16 v[116:119], v[132:135], v[202:205], v[116:119]
	v_mfma_f32_16x16x32_bf16 v[112:115], v[164:167], v[202:205], v[112:115]
	v_mfma_f32_16x16x32_bf16 v[100:103], v[132:135], v[212:215], v[100:103]
	v_mfma_f32_16x16x32_bf16 v[96:99], v[164:167], v[212:215], v[96:99]
	v_mfma_f32_16x16x32_bf16 v[84:87], v[132:135], v[220:223], v[84:87]
	v_mfma_f32_16x16x32_bf16 v[80:83], v[164:167], v[220:223], v[80:83]
	v_mfma_f32_16x16x32_bf16 v[108:111], v[168:171], v[190:193], v[108:111]
	v_mfma_f32_16x16x32_bf16 v[104:107], v[182:185], v[190:193], v[104:107]
	v_mfma_f32_16x16x32_bf16 v[92:95], v[168:171], v[198:201], v[92:95]
	v_mfma_f32_16x16x32_bf16 v[88:91], v[182:185], v[198:201], v[88:91]
	v_mfma_f32_16x16x32_bf16 v[76:79], v[168:171], v[206:209], v[76:79]
	v_mfma_f32_16x16x32_bf16 v[72:75], v[182:185], v[206:209], v[72:75]
	v_mfma_f32_16x16x32_bf16 v[68:71], v[168:171], v[216:219], v[68:71]
	v_mfma_f32_16x16x32_bf16 v[64:67], v[182:185], v[216:219], v[64:67]
	v_mfma_f32_16x16x32_bf16 v[108:111], v[172:175], v[194:197], v[108:111]
	v_mfma_f32_16x16x32_bf16 v[104:107], v[186:189], v[194:197], v[104:107]
	v_mfma_f32_16x16x32_bf16 v[92:95], v[172:175], v[202:205], v[92:95]
	v_mfma_f32_16x16x32_bf16 v[88:91], v[186:189], v[202:205], v[88:91]
	v_mfma_f32_16x16x32_bf16 v[76:79], v[172:175], v[212:215], v[76:79]
	v_mfma_f32_16x16x32_bf16 v[72:75], v[186:189], v[212:215], v[72:75]
	v_mfma_f32_16x16x32_bf16 v[68:71], v[172:175], v[220:223], v[68:71]
	v_mfma_f32_16x16x32_bf16 v[64:67], v[186:189], v[220:223], v[64:67]
	s_barrier
	s_add_i32 vcc_hi, s42, s83
	v_lshl_add_u64 v[178:179], s[98:99], 0, v[142:143]
	s_mov_b32 m0, vcc_hi
	ds_read_b128 v[190:193], v181 offset:16384
	ds_read_b128 v[194:197], v181 offset:17408
	ds_read_b128 v[198:201], v181 offset:18432
	ds_read_b128 v[202:205], v181 offset:19456
	ds_read_b128 v[206:209], v181 offset:20480
	ds_read_b128 v[212:215], v181 offset:21504
	ds_read_b128 v[216:219], v181 offset:22528
	ds_read_b128 v[220:223], v181 offset:23552
	global_load_lds_dwordx4 v[178:179], off
	s_add_i32 m0, vcc_hi, 0x2000
	v_lshl_add_u64 v[224:225], s[98:99], 0, v[146:147]
	s_add_u32 s98, s98, s18
	s_addc_u32 s99, s99, 0
	s_add_i32 vcc_lo, vcc_lo, s83
	global_load_lds_dwordx4 v[224:225], off
	v_lshl_add_u64 v[226:227], s[98:99], 0, v[142:143]
	s_mov_b32 m0, vcc_lo
	v_lshl_add_u64 v[228:229], s[98:99], 0, v[146:147]
	global_load_lds_dwordx4 v[226:227], off
	s_add_i32 m0, vcc_lo, 0x2000
	v_lshl_add_u64 v[230:231], s[38:39], 0, v[140:141]
	global_load_lds_dwordx4 v[228:229], off
	s_mov_b32 m0, s36
	v_lshl_add_u64 v[232:233], s[38:39], 0, v[144:145]
	global_load_lds_dwordx4 v[230:231], off
	s_mov_b32 m0, s10
	s_nop 0
	global_load_lds_dwordx4 v[232:233], off
	s_waitcnt vmcnt(8)
	s_waitcnt lgkmcnt(0)
	s_barrier
; #define PG8_STAGE(bufoff, gbase, voff) do { _Pragma("unroll") for (int _i = 0; _i < 2; ++_i) \
;         __builtin_amdgcn_global_load_lds((const unsigned*)((const char*)(gbase) + (voff)[_i]), (PG8_LAS unsigned*)(lds + (bufoff) + ldsw + _i * 8192), 16, 0, 0); } while (0)
; #define PG8_LDA(dst, b, h) do { _Pragma("unroll") for (int m = 0; m < 4; ++m) _Pragma("unroll") for (int k = 0; k < 2; ++k) dst[m][k] = *(const PG8_LAS bf16x8*)(lds + PG8_SA(b, h) + aoff + m * 2048 + k * 1024); } while (0)
; #define PG8_LDB(dst, b, h) do { _Pragma("unroll") for (int n = 0; n < 2; ++n) _Pragma("unroll") for (int k = 0; k < 2; ++k) dst[n][k] = *(const PG8_LAS bf16x8*)(lds + PG8_SB(b, h) + boff + n * 2048 + k * 1024); } while (0)
; #define PG8_MMA(ai, bj, At, Bt) do { __builtin_amdgcn_s_setprio(1); _Pragma("unroll") for (int m = 0; m < 4; ++m) _Pragma("unroll") for (int n = 0; n < 2; ++n) _Pragma("unroll") for (int k = 0; k < 2; ++k) \
;         acc[ai][bj][m][n] = __builtin_amdgcn_mfma_f32_16x16x32_bf16(Bt[n][k], At[m][k], acc[ai][bj][m][n], 0, 0, 0); __builtin_amdgcn_s_setprio(0); } while (0)
; #define PG8_WAIT_V(n) asm volatile("s_waitcnt vmcnt(" #n ")" ::: "memory")
; #define PG8_WAIT_L(n) asm volatile("s_waitcnt lgkmcnt(" #n ")" ::: "memory")
; #define PG8_BAR __builtin_amdgcn_s_barrier()
; #define PG8_SCHED __builtin_amdgcn_sched_barrier(0)
; template <class Epi, class Sched, bool ALIGN_EPI = false, bool SP2 = false>
; __device__ __forceinline__ void gemm_phase(PG8_LAS unsigned char* lds, const Gemm g, const Sched& S, const Epi& E, const int wid_) {
;     ...
;             PG8_WAIT_V(8); PG8_WAIT_L(0); PG8_BAR; PG8_MMA(1, 0, At, B0); PG8_MMA(1, 1, At, B1); PG8_BAR; PG8_SCHED;
;             PG8_LDB(B0, 1, 0); PG8_LDB(B1, 1, 1); PG8_SCHED; PG8_LDA(At, 1, 0); PG8_STAGE(PG8_SA(0, 1), a2 + hstepA, voffA);
;             PG8_WAIT_V(8); PG8_WAIT_L(0); PG8_BAR; PG8_MMA(0, 0, At, B0); PG8_MMA(0, 1, At, B1); PG8_BAR; PG8_SCHED;
;             PG8_LDA(At, 1, 1); PG8_STAGE(PG8_SB(1, 0), b3, voffB); PG8_STAGE(PG8_SB(1, 1), b3 + hstepB, voffB); PG8_STAGE(PG8_SA(1, 0), a3, voffA);
	s_waitcnt lgkmcnt(0)
	v_mfma_f32_16x16x32_bf16 v[60:63], v[128:131], v[190:193], v[60:63]
	v_mfma_f32_16x16x32_bf16 v[56:59], v[136:139], v[190:193], v[56:59]
	v_mfma_f32_16x16x32_bf16 v[52:55], v[128:131], v[198:201], v[52:55]
	v_mfma_f32_16x16x32_bf16 v[48:51], v[136:139], v[198:201], v[48:51]
	v_mfma_f32_16x16x32_bf16 v[36:39], v[128:131], v[206:209], v[36:39]
	v_mfma_f32_16x16x32_bf16 v[32:35], v[136:139], v[206:209], v[32:35]
	v_mfma_f32_16x16x32_bf16 v[20:23], v[128:131], v[216:219], v[20:23]
	v_mfma_f32_16x16x32_bf16 v[16:19], v[136:139], v[216:219], v[16:19]
	v_mfma_f32_16x16x32_bf16 v[60:63], v[132:135], v[194:197], v[60:63]
	v_mfma_f32_16x16x32_bf16 v[56:59], v[164:167], v[194:197], v[56:59]
	v_mfma_f32_16x16x32_bf16 v[52:55], v[132:135], v[202:205], v[52:55]
	v_mfma_f32_16x16x32_bf16 v[48:51], v[164:167], v[202:205], v[48:51]
	v_mfma_f32_16x16x32_bf16 v[36:39], v[132:135], v[212:215], v[36:39]
	v_mfma_f32_16x16x32_bf16 v[32:35], v[164:167], v[212:215], v[32:35]
	v_mfma_f32_16x16x32_bf16 v[20:23], v[132:135], v[220:223], v[20:23]
	v_mfma_f32_16x16x32_bf16 v[16:19], v[164:167], v[220:223], v[16:19]
	v_mfma_f32_16x16x32_bf16 v[44:47], v[168:171], v[190:193], v[44:47]
	v_mfma_f32_16x16x32_bf16 v[40:43], v[182:185], v[190:193], v[40:43]
	v_mfma_f32_16x16x32_bf16 v[28:31], v[168:171], v[198:201], v[28:31]
	v_mfma_f32_16x16x32_bf16 v[24:27], v[182:185], v[198:201], v[24:27]
	v_mfma_f32_16x16x32_bf16 v[12:15], v[168:171], v[206:209], v[12:15]
	v_mfma_f32_16x16x32_bf16 v[8:11], v[182:185], v[206:209], v[8:11]
	v_mfma_f32_16x16x32_bf16 v[4:7], v[168:171], v[216:219], v[4:7]
	v_mfma_f32_16x16x32_bf16 v[0:3], v[182:185], v[216:219], v[0:3]
	v_mfma_f32_16x16x32_bf16 v[44:47], v[172:175], v[194:197], v[44:47]
	v_mfma_f32_16x16x32_bf16 v[40:43], v[186:189], v[194:197], v[40:43]
	v_mfma_f32_16x16x32_bf16 v[28:31], v[172:175], v[202:205], v[28:31]
	v_mfma_f32_16x16x32_bf16 v[24:27], v[186:189], v[202:205], v[24:27]
	v_mfma_f32_16x16x32_bf16 v[12:15], v[172:175], v[212:215], v[12:15]
	v_mfma_f32_16x16x32_bf16 v[8:11], v[186:189], v[212:215], v[8:11]
	v_mfma_f32_16x16x32_bf16 v[4:7], v[172:175], v[220:223], v[4:7]
	v_mfma_f32_16x16x32_bf16 v[0:3], v[186:189], v[220:223], v[0:3]
	s_barrier
	s_add_i32 s98, 0, 0x18000
	s_add_i32 s99, 0, 0x1c000
	v_add_u32_e32 v164, s98, v180
	v_add_u32_e32 v176, s99, v180
	ds_read_b128 v[128:131], v164
	ds_read_b128 v[132:135], v164 offset:1024
	ds_read_b128 v[136:139], v164 offset:2048
	ds_read_b128 v[164:167], v164 offset:3072
	ds_read_b128 v[168:171], v176
	ds_read_b128 v[172:175], v176 offset:1024
	ds_read_b128 v[182:185], v176 offset:2048
	ds_read_b128 v[186:189], v176 offset:3072
	s_add_u32 s38, s38, s88
	s_addc_u32 s39, s39, 0
	s_mov_b32 m0, s11
	v_lshl_add_u64 v[234:235], s[38:39], 0, v[140:141]
	ds_read_b128 v[190:193], v181 offset:32768
	ds_read_b128 v[194:197], v181 offset:33792
	ds_read_b128 v[198:201], v181 offset:34816
	ds_read_b128 v[202:205], v181 offset:35840
	ds_read_b128 v[206:209], v181 offset:36864
	ds_read_b128 v[212:215], v181 offset:37888
	ds_read_b128 v[216:219], v181 offset:38912
	ds_read_b128 v[220:223], v181 offset:39936
	global_load_lds_dwordx4 v[234:235], off
	v_lshl_add_u64 v[234:235], s[38:39], 0, v[144:145]
	s_mov_b32 m0, s55
	s_nop 0
	global_load_lds_dwordx4 v[234:235], off
	s_waitcnt vmcnt(8)
	s_waitcnt lgkmcnt(0)
	s_barrier
	s_waitcnt lgkmcnt(0)
	v_mfma_f32_16x16x32_bf16 v[124:127], v[128:131], v[190:193], v[124:127]
	v_mfma_f32_16x16x32_bf16 v[120:123], v[136:139], v[190:193], v[120:123]
	v_mfma_f32_16x16x32_bf16 v[116:119], v[128:131], v[198:201], v[116:119]
	v_mfma_f32_16x16x32_bf16 v[112:115], v[136:139], v[198:201], v[112:115]
	v_mfma_f32_16x16x32_bf16 v[100:103], v[128:131], v[206:209], v[100:103]
	v_mfma_f32_16x16x32_bf16 v[96:99], v[136:139], v[206:209], v[96:99]
	v_mfma_f32_16x16x32_bf16 v[84:87], v[128:131], v[216:219], v[84:87]
	v_mfma_f32_16x16x32_bf16 v[80:83], v[136:139], v[216:219], v[80:83]
	v_mfma_f32_16x16x32_bf16 v[124:127], v[132:135], v[194:197], v[124:127]
	v_mfma_f32_16x16x32_bf16 v[120:123], v[164:167], v[194:197], v[120:123]
	v_mfma_f32_16x16x32_bf16 v[116:119], v[132:135], v[202:205], v[116:119]
	v_mfma_f32_16x16x32_bf16 v[112:115], v[164:167], v[202:205], v[112:115]
	v_mfma_f32_16x16x32_bf16 v[100:103], v[132:135], v[212:215], v[100:103]
	v_mfma_f32_16x16x32_bf16 v[96:99], v[164:167], v[212:215], v[96:99]
	v_mfma_f32_16x16x32_bf16 v[84:87], v[132:135], v[220:223], v[84:87]
	v_mfma_f32_16x16x32_bf16 v[80:83], v[164:167], v[220:223], v[80:83]
	v_mfma_f32_16x16x32_bf16 v[108:111], v[168:171], v[190:193], v[108:111]
	v_mfma_f32_16x16x32_bf16 v[104:107], v[182:185], v[190:193], v[104:107]
	v_mfma_f32_16x16x32_bf16 v[92:95], v[168:171], v[198:201], v[92:95]
	v_mfma_f32_16x16x32_bf16 v[88:91], v[182:185], v[198:201], v[88:91]
	v_mfma_f32_16x16x32_bf16 v[76:79], v[168:171], v[206:209], v[76:79]
	v_mfma_f32_16x16x32_bf16 v[72:75], v[182:185], v[206:209], v[72:75]
	v_mfma_f32_16x16x32_bf16 v[68:71], v[168:171], v[216:219], v[68:71]
	v_mfma_f32_16x16x32_bf16 v[64:67], v[182:185], v[216:219], v[64:67]
	v_mfma_f32_16x16x32_bf16 v[108:111], v[172:175], v[194:197], v[108:111]
	v_mfma_f32_16x16x32_bf16 v[104:107], v[186:189], v[194:197], v[104:107]
	v_mfma_f32_16x16x32_bf16 v[92:95], v[172:175], v[202:205], v[92:95]
	v_mfma_f32_16x16x32_bf16 v[88:91], v[186:189], v[202:205], v[88:91]
	v_mfma_f32_16x16x32_bf16 v[76:79], v[172:175], v[212:215], v[76:79]
	v_mfma_f32_16x16x32_bf16 v[72:75], v[186:189], v[212:215], v[72:75]
	v_mfma_f32_16x16x32_bf16 v[68:71], v[172:175], v[220:223], v[68:71]
	v_mfma_f32_16x16x32_bf16 v[64:67], v[186:189], v[220:223], v[64:67]
	s_barrier
; #define PG8_STAGE(bufoff, gbase, voff) do { _Pragma("unroll") for (int _i = 0; _i < 2; ++_i) \
;         __builtin_amdgcn_global_load_lds((const unsigned*)((const char*)(gbase) + (voff)[_i]), (PG8_LAS unsigned*)(lds + (bufoff) + ldsw + _i * 8192), 16, 0, 0); } while (0)
; #define PG8_LDA(dst, b, h) do { _Pragma("unroll") for (int m = 0; m < 4; ++m) _Pragma("unroll") for (int k = 0; k < 2; ++k) dst[m][k] = *(const PG8_LAS bf16x8*)(lds + PG8_SA(b, h) + aoff + m * 2048 + k * 1024); } while (0)
; #define PG8_MMA(ai, bj, At, Bt) do { __builtin_amdgcn_s_setprio(1); _Pragma("unroll") for (int m = 0; m < 4; ++m) _Pragma("unroll") for (int n = 0; n < 2; ++n) _Pragma("unroll") for (int k = 0; k < 2; ++k) \
;         acc[ai][bj][m][n] = __builtin_amdgcn_mfma_f32_16x16x32_bf16(Bt[n][k], At[m][k], acc[ai][bj][m][n], 0, 0, 0); __builtin_amdgcn_s_setprio(0); } while (0)
; #define PG8_WAIT_V(n) asm volatile("s_waitcnt vmcnt(" #n ")" ::: "memory")
; #define PG8_WAIT_L(n) asm volatile("s_waitcnt lgkmcnt(" #n ")" ::: "memory")
; #define PG8_BAR __builtin_amdgcn_s_barrier()
; #define PG8_SCHED __builtin_amdgcn_sched_barrier(0)
; template <class Epi, class Sched, bool ALIGN_EPI = false, bool SP2 = false>
; __device__ __forceinline__ void gemm_phase(PG8_LAS unsigned char* lds, const Gemm g, const Sched& S, const Epi& E, const int wid_) {
;     ...
;             PG8_LDA(At, 1, 1); PG8_STAGE(PG8_SB(1, 0), b3, voffB); PG8_STAGE(PG8_SB(1, 1), b3 + hstepB, voffB); PG8_STAGE(PG8_SA(1, 0), a3, voffA);
;             PG8_WAIT_V(8); PG8_WAIT_L(0); PG8_BAR; PG8_MMA(1, 0, At, B0); PG8_MMA(1, 1, At, B1); PG8_BAR; PG8_SCHED;
;     ...
;         if constexpr (ALIGN_EPI) { if (wr == 0) PG8_BAR; }
;         if constexpr (!Epi::AFTER_DRAIN) { E(acc, cur, wr, wc, fr, fq); S.done(cur); }
	s_add_i32 s38, s98, s83
	v_lshl_add_u64 v[178:179], v[178:179], 0, s[66:67]
	s_mov_b32 m0, s38
	ds_read_b128 v[190:193], v181 offset:49152
	ds_read_b128 v[194:197], v181 offset:50176
	ds_read_b128 v[198:201], v181 offset:51200
	ds_read_b128 v[202:205], v181 offset:52224
	ds_read_b128 v[206:209], v181 offset:53248
	ds_read_b128 v[212:215], v181 offset:54272
	ds_read_b128 v[216:219], v181 offset:55296
	ds_read_b128 v[220:223], v181 offset:56320
	global_load_lds_dwordx4 v[178:179], off
	v_lshl_add_u64 v[178:179], v[224:225], 0, s[66:67]
	s_add_i32 m0, s38, 0x2000
	s_add_i32 s38, s99, s83
	global_load_lds_dwordx4 v[178:179], off
	v_lshl_add_u64 v[178:179], v[226:227], 0, s[66:67]
	s_mov_b32 m0, s38
	s_nop 0
	global_load_lds_dwordx4 v[178:179], off
	v_lshl_add_u64 v[178:179], v[228:229], 0, s[66:67]
	s_add_i32 m0, s38, 0x2000
	s_nop 0
	global_load_lds_dwordx4 v[178:179], off
	v_lshl_add_u64 v[178:179], v[230:231], 0, s[66:67]
	s_mov_b32 m0, s33
	s_nop 0
	global_load_lds_dwordx4 v[178:179], off
	v_lshl_add_u64 v[178:179], v[232:233], 0, s[66:67]
	s_mov_b32 m0, s52
	s_nop 0
	global_load_lds_dwordx4 v[178:179], off
	s_waitcnt vmcnt(8)
	s_waitcnt lgkmcnt(0)
	s_barrier
	s_waitcnt lgkmcnt(0)
	v_mfma_f32_16x16x32_bf16 v[60:63], v[128:131], v[190:193], v[60:63]
	v_mfma_f32_16x16x32_bf16 v[56:59], v[136:139], v[190:193], v[56:59]
	v_mfma_f32_16x16x32_bf16 v[52:55], v[128:131], v[198:201], v[52:55]
	v_mfma_f32_16x16x32_bf16 v[48:51], v[136:139], v[198:201], v[48:51]
	v_mfma_f32_16x16x32_bf16 v[36:39], v[128:131], v[206:209], v[36:39]
	v_mfma_f32_16x16x32_bf16 v[32:35], v[136:139], v[206:209], v[32:35]
	v_mfma_f32_16x16x32_bf16 v[20:23], v[128:131], v[216:219], v[20:23]
	v_mfma_f32_16x16x32_bf16 v[16:19], v[136:139], v[216:219], v[16:19]
	v_mfma_f32_16x16x32_bf16 v[60:63], v[132:135], v[194:197], v[60:63]
	v_mfma_f32_16x16x32_bf16 v[56:59], v[164:167], v[194:197], v[56:59]
	v_mfma_f32_16x16x32_bf16 v[52:55], v[132:135], v[202:205], v[52:55]
	v_mfma_f32_16x16x32_bf16 v[48:51], v[164:167], v[202:205], v[48:51]
	v_mfma_f32_16x16x32_bf16 v[36:39], v[132:135], v[212:215], v[36:39]
	v_mfma_f32_16x16x32_bf16 v[32:35], v[164:167], v[212:215], v[32:35]
	v_mfma_f32_16x16x32_bf16 v[20:23], v[132:135], v[220:223], v[20:23]
	v_mfma_f32_16x16x32_bf16 v[16:19], v[164:167], v[220:223], v[16:19]
	v_mfma_f32_16x16x32_bf16 v[44:47], v[168:171], v[190:193], v[44:47]
	v_mfma_f32_16x16x32_bf16 v[40:43], v[182:185], v[190:193], v[40:43]
	v_mfma_f32_16x16x32_bf16 v[28:31], v[168:171], v[198:201], v[28:31]
	v_mfma_f32_16x16x32_bf16 v[24:27], v[182:185], v[198:201], v[24:27]
	v_mfma_f32_16x16x32_bf16 v[12:15], v[168:171], v[206:209], v[12:15]
	v_mfma_f32_16x16x32_bf16 v[8:11], v[182:185], v[206:209], v[8:11]
	v_mfma_f32_16x16x32_bf16 v[4:7], v[168:171], v[216:219], v[4:7]
	v_mfma_f32_16x16x32_bf16 v[0:3], v[182:185], v[216:219], v[0:3]
	v_mfma_f32_16x16x32_bf16 v[44:47], v[172:175], v[194:197], v[44:47]
	v_mfma_f32_16x16x32_bf16 v[40:43], v[186:189], v[194:197], v[40:43]
	v_mfma_f32_16x16x32_bf16 v[28:31], v[172:175], v[202:205], v[28:31]
	v_mfma_f32_16x16x32_bf16 v[24:27], v[186:189], v[202:205], v[24:27]
	v_mfma_f32_16x16x32_bf16 v[12:15], v[172:175], v[212:215], v[12:15]
	v_mfma_f32_16x16x32_bf16 v[8:11], v[186:189], v[212:215], v[8:11]
	v_mfma_f32_16x16x32_bf16 v[4:7], v[172:175], v[220:223], v[4:7]
	v_mfma_f32_16x16x32_bf16 v[0:3], v[186:189], v[220:223], v[0:3]
	s_barrier
	s_add_u32 s49, s49, 0x100
	s_addc_u32 s62, s62, 0
	s_add_u32 s6, s6, 0x100
	s_addc_u32 s7, s7, 0
	s_cmp_ge_u32 s97, s71
	s_mov_b32 s38, s97
	s_cbranch_scc0 .LBB0_380
	s_setprio 0
	s_and_b64 vcc, exec, s[94:95]
	s_cbranch_vccz .LBB0_384
	s_barrier
	v_lshl_add_u32 v164, s48, 8, v153
	s_cmp_lt_i32 s37, 2
	s_mov_b64 s[6:7], -1
	s_cbranch_scc0 .LBB0_385
